# up/down K-loops: zig-zag k order in the accumulate chains (every chain boundary keeps one operand register); f32 accumulation order of the two k-steps swapped for half the accumulators
# baseline (speedup 1.0000x reference)
.LBB0_535:
	ds_read_b128 v[150:153], v128
	ds_read_b128 v[154:157], v128 offset:1024
	ds_read_b128 v[158:161], v128 offset:2048
	ds_read_b128 v[170:173], v128 offset:3072
	ds_read_b128 v[174:177], v146
	ds_read_b128 v[178:181], v146 offset:1024
	ds_read_b128 v[182:185], v146 offset:2048
	ds_read_b128 v[186:189], v146 offset:3072
	s_cmp_eq_u32 s16, 60
	s_cselect_b32 s62, s94, vcc_lo
	s_cselect_b32 s63, s53, vcc_hi
	s_cselect_b32 s60, s95, s14
	s_cselect_b32 s61, s41, s15
	s_add_u32 s58, s62, 0x8000
	s_addc_u32 s59, s63, 0
	ds_read_b128 v[190:193], v147
	ds_read_b128 v[194:197], v147 offset:1024
	ds_read_b128 v[198:201], v147 offset:2048
	ds_read_b128 v[202:205], v147 offset:3072
	ds_read_b128 v[206:209], v147 offset:4096
	ds_read_b128 v[210:213], v147 offset:5120
	ds_read_b128 v[214:217], v147 offset:6144
	ds_read_b128 v[218:221], v147 offset:7168
	s_add_u32 s18, vcc_lo, 0xffffc000
	s_addc_u32 s19, vcc_hi, -1
	s_mov_b32 m0, s89
	s_nop 0
	global_load_lds_dwordx4 v142, s[18:19]
	s_nop 0
	s_mov_b32 m0, s90
	s_nop 0
	global_load_lds_dwordx4 v144, s[18:19]
	s_waitcnt vmcnt(8)
	s_waitcnt lgkmcnt(0)
	s_setprio 1
	s_barrier
	v_mfma_f32_16x16x32_bf16 v[124:127], v[150:153], v[190:193], v[124:127]
	v_mfma_f32_16x16x32_bf16 v[124:127], v[154:157], v[194:197], v[124:127]
	v_mfma_f32_16x16x32_bf16 v[120:123], v[170:173], v[194:197], v[120:123]
	v_mfma_f32_16x16x32_bf16 v[120:123], v[158:161], v[190:193], v[120:123]
	v_mfma_f32_16x16x32_bf16 v[104:107], v[158:161], v[198:201], v[104:107]
	v_mfma_f32_16x16x32_bf16 v[104:107], v[170:173], v[202:205], v[104:107]
	v_mfma_f32_16x16x32_bf16 v[108:111], v[154:157], v[202:205], v[108:111]
	v_mfma_f32_16x16x32_bf16 v[108:111], v[150:153], v[198:201], v[108:111]
	v_mfma_f32_16x16x32_bf16 v[92:95], v[150:153], v[206:209], v[92:95]
	v_mfma_f32_16x16x32_bf16 v[92:95], v[154:157], v[210:213], v[92:95]
	v_mfma_f32_16x16x32_bf16 v[88:91], v[170:173], v[210:213], v[88:91]
	v_mfma_f32_16x16x32_bf16 v[88:91], v[158:161], v[206:209], v[88:91]
	v_mfma_f32_16x16x32_bf16 v[72:75], v[158:161], v[214:217], v[72:75]
	v_mfma_f32_16x16x32_bf16 v[72:75], v[170:173], v[218:221], v[72:75]
	v_mfma_f32_16x16x32_bf16 v[76:79], v[154:157], v[218:221], v[76:79]
	v_mfma_f32_16x16x32_bf16 v[76:79], v[150:153], v[214:217], v[76:79]
	s_setprio 0
	s_setprio 1
	v_mfma_f32_16x16x32_bf16 v[116:119], v[174:177], v[190:193], v[116:119]
	v_mfma_f32_16x16x32_bf16 v[116:119], v[178:181], v[194:197], v[116:119]
	v_mfma_f32_16x16x32_bf16 v[112:115], v[186:189], v[194:197], v[112:115]
	v_mfma_f32_16x16x32_bf16 v[112:115], v[182:185], v[190:193], v[112:115]
	v_mfma_f32_16x16x32_bf16 v[96:99], v[182:185], v[198:201], v[96:99]
	v_mfma_f32_16x16x32_bf16 v[96:99], v[186:189], v[202:205], v[96:99]
	v_mfma_f32_16x16x32_bf16 v[100:103], v[178:181], v[202:205], v[100:103]
	v_mfma_f32_16x16x32_bf16 v[100:103], v[174:177], v[198:201], v[100:103]
	v_mfma_f32_16x16x32_bf16 v[84:87], v[174:177], v[206:209], v[84:87]
	v_mfma_f32_16x16x32_bf16 v[84:87], v[178:181], v[210:213], v[84:87]
	v_mfma_f32_16x16x32_bf16 v[80:83], v[186:189], v[210:213], v[80:83]
	v_mfma_f32_16x16x32_bf16 v[80:83], v[182:185], v[206:209], v[80:83]
	v_mfma_f32_16x16x32_bf16 v[64:67], v[182:185], v[214:217], v[64:67]
	v_mfma_f32_16x16x32_bf16 v[64:67], v[186:189], v[218:221], v[64:67]
	v_mfma_f32_16x16x32_bf16 v[68:71], v[178:181], v[218:221], v[68:71]
	v_mfma_f32_16x16x32_bf16 v[68:71], v[174:177], v[214:217], v[68:71]
	s_setprio 0
	s_barrier
	ds_read_b128 v[190:193], v147 offset:16384
	ds_read_b128 v[194:197], v147 offset:17408
	ds_read_b128 v[198:201], v147 offset:18432
	ds_read_b128 v[202:205], v147 offset:19456
	ds_read_b128 v[206:209], v147 offset:20480
	ds_read_b128 v[210:213], v147 offset:21504
	ds_read_b128 v[214:217], v147 offset:22528
	ds_read_b128 v[218:221], v147 offset:23552
	s_mov_b32 m0, s45
	s_nop 0
	global_load_lds_dwordx4 v143, s[60:61]
	s_add_u32 s18, s60, 0x4000
	s_mov_b32 m0, s46
	s_nop 0
	global_load_lds_dwordx4 v145, s[60:61]
	s_addc_u32 s19, s61, 0
	s_mov_b32 m0, s47
	s_nop 0
	global_load_lds_dwordx4 v143, s[18:19]
	s_nop 0
	s_mov_b32 m0, s64
	s_nop 0
	global_load_lds_dwordx4 v145, s[18:19]
	s_nop 0
	s_mov_b32 m0, s44
	s_nop 0
	global_load_lds_dwordx4 v142, s[62:63]
	s_nop 0
	s_mov_b32 m0, s65
	s_nop 0
	global_load_lds_dwordx4 v144, s[62:63]
	s_waitcnt vmcnt(8)
	s_waitcnt lgkmcnt(0)
	s_setprio 1
	s_barrier
	v_mfma_f32_16x16x32_bf16 v[60:63], v[150:153], v[190:193], v[60:63]
	v_mfma_f32_16x16x32_bf16 v[60:63], v[154:157], v[194:197], v[60:63]
	v_mfma_f32_16x16x32_bf16 v[56:59], v[170:173], v[194:197], v[56:59]
	v_mfma_f32_16x16x32_bf16 v[56:59], v[158:161], v[190:193], v[56:59]
	v_mfma_f32_16x16x32_bf16 v[40:43], v[158:161], v[198:201], v[40:43]
	v_mfma_f32_16x16x32_bf16 v[40:43], v[170:173], v[202:205], v[40:43]
	v_mfma_f32_16x16x32_bf16 v[44:47], v[154:157], v[202:205], v[44:47]
	v_mfma_f32_16x16x32_bf16 v[44:47], v[150:153], v[198:201], v[44:47]
	v_mfma_f32_16x16x32_bf16 v[28:31], v[150:153], v[206:209], v[28:31]
	v_mfma_f32_16x16x32_bf16 v[28:31], v[154:157], v[210:213], v[28:31]
	v_mfma_f32_16x16x32_bf16 v[24:27], v[170:173], v[210:213], v[24:27]
	v_mfma_f32_16x16x32_bf16 v[24:27], v[158:161], v[206:209], v[24:27]
	v_mfma_f32_16x16x32_bf16 v[8:11], v[158:161], v[214:217], v[8:11]
	v_mfma_f32_16x16x32_bf16 v[8:11], v[170:173], v[218:221], v[8:11]
	v_mfma_f32_16x16x32_bf16 v[12:15], v[154:157], v[218:221], v[12:15]
	v_mfma_f32_16x16x32_bf16 v[12:15], v[150:153], v[214:217], v[12:15]
	s_setprio 0
	s_setprio 1
	v_mfma_f32_16x16x32_bf16 v[52:55], v[174:177], v[190:193], v[52:55]
	v_mfma_f32_16x16x32_bf16 v[52:55], v[178:181], v[194:197], v[52:55]
	v_mfma_f32_16x16x32_bf16 v[48:51], v[186:189], v[194:197], v[48:51]
	v_mfma_f32_16x16x32_bf16 v[48:51], v[182:185], v[190:193], v[48:51]
	v_mfma_f32_16x16x32_bf16 v[32:35], v[182:185], v[198:201], v[32:35]
	v_mfma_f32_16x16x32_bf16 v[32:35], v[186:189], v[202:205], v[32:35]
	v_mfma_f32_16x16x32_bf16 v[36:39], v[178:181], v[202:205], v[36:39]
	v_mfma_f32_16x16x32_bf16 v[36:39], v[174:177], v[198:201], v[36:39]
	v_mfma_f32_16x16x32_bf16 v[20:23], v[174:177], v[206:209], v[20:23]
	v_mfma_f32_16x16x32_bf16 v[20:23], v[178:181], v[210:213], v[20:23]
	v_mfma_f32_16x16x32_bf16 v[16:19], v[186:189], v[210:213], v[16:19]
	v_mfma_f32_16x16x32_bf16 v[16:19], v[182:185], v[206:209], v[16:19]
	v_mfma_f32_16x16x32_bf16 v[0:3], v[182:185], v[214:217], v[0:3]
	v_mfma_f32_16x16x32_bf16 v[0:3], v[186:189], v[218:221], v[0:3]
	v_mfma_f32_16x16x32_bf16 v[4:7], v[178:181], v[218:221], v[4:7]
	v_mfma_f32_16x16x32_bf16 v[4:7], v[174:177], v[214:217], v[4:7]
	s_setprio 0
	s_barrier
	ds_read_b128 v[150:153], v148
	ds_read_b128 v[154:157], v148 offset:1024
	ds_read_b128 v[158:161], v148 offset:2048
	ds_read_b128 v[170:173], v148 offset:3072
	ds_read_b128 v[174:177], v149
	ds_read_b128 v[178:181], v149 offset:1024
	ds_read_b128 v[182:185], v149 offset:2048
	ds_read_b128 v[186:189], v149 offset:3072
	ds_read_b128 v[190:193], v147 offset:32768
	ds_read_b128 v[194:197], v147 offset:33792
	ds_read_b128 v[198:201], v147 offset:34816
	ds_read_b128 v[202:205], v147 offset:35840
	ds_read_b128 v[206:209], v147 offset:36864
	ds_read_b128 v[210:213], v147 offset:37888
	ds_read_b128 v[214:217], v147 offset:38912
	ds_read_b128 v[218:221], v147 offset:39936
	s_add_u32 s18, s62, 0x4000
	s_addc_u32 s19, s63, 0
	s_mov_b32 m0, s66
	s_nop 0
	global_load_lds_dwordx4 v142, s[18:19]
	s_nop 0
	s_mov_b32 m0, s67
	s_nop 0
	global_load_lds_dwordx4 v144, s[18:19]
	s_waitcnt vmcnt(8)
	s_waitcnt lgkmcnt(0)
	s_setprio 1
	s_barrier
	v_mfma_f32_16x16x32_bf16 v[124:127], v[150:153], v[190:193], v[124:127]
	v_mfma_f32_16x16x32_bf16 v[124:127], v[154:157], v[194:197], v[124:127]
	v_mfma_f32_16x16x32_bf16 v[120:123], v[170:173], v[194:197], v[120:123]
	v_mfma_f32_16x16x32_bf16 v[120:123], v[158:161], v[190:193], v[120:123]
	v_mfma_f32_16x16x32_bf16 v[104:107], v[158:161], v[198:201], v[104:107]
	v_mfma_f32_16x16x32_bf16 v[104:107], v[170:173], v[202:205], v[104:107]
	v_mfma_f32_16x16x32_bf16 v[108:111], v[154:157], v[202:205], v[108:111]
	v_mfma_f32_16x16x32_bf16 v[108:111], v[150:153], v[198:201], v[108:111]
	v_mfma_f32_16x16x32_bf16 v[92:95], v[150:153], v[206:209], v[92:95]
	v_mfma_f32_16x16x32_bf16 v[92:95], v[154:157], v[210:213], v[92:95]
	v_mfma_f32_16x16x32_bf16 v[88:91], v[170:173], v[210:213], v[88:91]
	v_mfma_f32_16x16x32_bf16 v[88:91], v[158:161], v[206:209], v[88:91]
	v_mfma_f32_16x16x32_bf16 v[72:75], v[158:161], v[214:217], v[72:75]
	v_mfma_f32_16x16x32_bf16 v[72:75], v[170:173], v[218:221], v[72:75]
	v_mfma_f32_16x16x32_bf16 v[76:79], v[154:157], v[218:221], v[76:79]
	v_mfma_f32_16x16x32_bf16 v[76:79], v[150:153], v[214:217], v[76:79]
	s_setprio 0
	s_setprio 1
	v_mfma_f32_16x16x32_bf16 v[116:119], v[174:177], v[190:193], v[116:119]
	v_mfma_f32_16x16x32_bf16 v[116:119], v[178:181], v[194:197], v[116:119]
	v_mfma_f32_16x16x32_bf16 v[112:115], v[186:189], v[194:197], v[112:115]
	v_mfma_f32_16x16x32_bf16 v[112:115], v[182:185], v[190:193], v[112:115]
	v_mfma_f32_16x16x32_bf16 v[96:99], v[182:185], v[198:201], v[96:99]
	v_mfma_f32_16x16x32_bf16 v[96:99], v[186:189], v[202:205], v[96:99]
	v_mfma_f32_16x16x32_bf16 v[100:103], v[178:181], v[202:205], v[100:103]
	v_mfma_f32_16x16x32_bf16 v[100:103], v[174:177], v[198:201], v[100:103]
	v_mfma_f32_16x16x32_bf16 v[84:87], v[174:177], v[206:209], v[84:87]
	v_mfma_f32_16x16x32_bf16 v[84:87], v[178:181], v[210:213], v[84:87]
	v_mfma_f32_16x16x32_bf16 v[80:83], v[186:189], v[210:213], v[80:83]
	v_mfma_f32_16x16x32_bf16 v[80:83], v[182:185], v[206:209], v[80:83]
	v_mfma_f32_16x16x32_bf16 v[64:67], v[182:185], v[214:217], v[64:67]
	v_mfma_f32_16x16x32_bf16 v[64:67], v[186:189], v[218:221], v[64:67]
	v_mfma_f32_16x16x32_bf16 v[68:71], v[178:181], v[218:221], v[68:71]
	v_mfma_f32_16x16x32_bf16 v[68:71], v[174:177], v[214:217], v[68:71]
	s_setprio 0
	s_barrier
	ds_read_b128 v[190:193], v147 offset:49152
	ds_read_b128 v[194:197], v147 offset:50176
	ds_read_b128 v[198:201], v147 offset:51200
	ds_read_b128 v[202:205], v147 offset:52224
	ds_read_b128 v[206:209], v147 offset:53248
	ds_read_b128 v[210:213], v147 offset:54272
	ds_read_b128 v[214:217], v147 offset:55296
	ds_read_b128 v[218:221], v147 offset:56320
	s_add_u32 s18, s60, 0x8000
	s_addc_u32 s19, s61, 0
	s_mov_b32 m0, s70
	s_nop 0
	global_load_lds_dwordx4 v143, s[18:19]
	s_nop 0
	s_mov_b32 m0, s71
	s_nop 0
	global_load_lds_dwordx4 v145, s[18:19]
	s_add_u32 s18, s60, 0xc000
	s_addc_u32 s19, s61, 0
	s_mov_b32 m0, s83
	s_nop 0
	global_load_lds_dwordx4 v143, s[18:19]
	s_nop 0
	s_mov_b32 m0, s88
	s_nop 0
	global_load_lds_dwordx4 v145, s[18:19]
	s_nop 0
	s_mov_b32 m0, s72
	s_nop 0
	global_load_lds_dwordx4 v142, s[58:59]
	s_nop 0
	s_mov_b32 m0, s81
	s_nop 0
	global_load_lds_dwordx4 v144, s[58:59]
	s_waitcnt vmcnt(8)
	s_waitcnt lgkmcnt(0)
	s_setprio 1
	s_barrier
	v_mfma_f32_16x16x32_bf16 v[60:63], v[150:153], v[190:193], v[60:63]
	v_mfma_f32_16x16x32_bf16 v[60:63], v[154:157], v[194:197], v[60:63]
	v_mfma_f32_16x16x32_bf16 v[56:59], v[170:173], v[194:197], v[56:59]
	v_mfma_f32_16x16x32_bf16 v[56:59], v[158:161], v[190:193], v[56:59]
	v_mfma_f32_16x16x32_bf16 v[40:43], v[158:161], v[198:201], v[40:43]
	v_mfma_f32_16x16x32_bf16 v[40:43], v[170:173], v[202:205], v[40:43]
	v_mfma_f32_16x16x32_bf16 v[44:47], v[154:157], v[202:205], v[44:47]
	v_mfma_f32_16x16x32_bf16 v[44:47], v[150:153], v[198:201], v[44:47]
	v_mfma_f32_16x16x32_bf16 v[28:31], v[150:153], v[206:209], v[28:31]
	v_mfma_f32_16x16x32_bf16 v[28:31], v[154:157], v[210:213], v[28:31]
	v_mfma_f32_16x16x32_bf16 v[24:27], v[170:173], v[210:213], v[24:27]
	v_mfma_f32_16x16x32_bf16 v[24:27], v[158:161], v[206:209], v[24:27]
	v_mfma_f32_16x16x32_bf16 v[8:11], v[158:161], v[214:217], v[8:11]
	v_mfma_f32_16x16x32_bf16 v[8:11], v[170:173], v[218:221], v[8:11]
	v_mfma_f32_16x16x32_bf16 v[12:15], v[154:157], v[218:221], v[12:15]
	v_mfma_f32_16x16x32_bf16 v[12:15], v[150:153], v[214:217], v[12:15]
	s_setprio 0
	s_setprio 1
	v_mfma_f32_16x16x32_bf16 v[52:55], v[174:177], v[190:193], v[52:55]
	v_mfma_f32_16x16x32_bf16 v[52:55], v[178:181], v[194:197], v[52:55]
	v_mfma_f32_16x16x32_bf16 v[48:51], v[186:189], v[194:197], v[48:51]
	v_mfma_f32_16x16x32_bf16 v[48:51], v[182:185], v[190:193], v[48:51]
	v_mfma_f32_16x16x32_bf16 v[32:35], v[182:185], v[198:201], v[32:35]
	v_mfma_f32_16x16x32_bf16 v[32:35], v[186:189], v[202:205], v[32:35]
	v_mfma_f32_16x16x32_bf16 v[36:39], v[178:181], v[202:205], v[36:39]
	v_mfma_f32_16x16x32_bf16 v[36:39], v[174:177], v[198:201], v[36:39]
	v_mfma_f32_16x16x32_bf16 v[20:23], v[174:177], v[206:209], v[20:23]
	v_mfma_f32_16x16x32_bf16 v[20:23], v[178:181], v[210:213], v[20:23]
	v_mfma_f32_16x16x32_bf16 v[16:19], v[186:189], v[210:213], v[16:19]
	v_mfma_f32_16x16x32_bf16 v[16:19], v[182:185], v[206:209], v[16:19]
	v_mfma_f32_16x16x32_bf16 v[0:3], v[182:185], v[214:217], v[0:3]
	v_mfma_f32_16x16x32_bf16 v[0:3], v[186:189], v[218:221], v[0:3]
	v_mfma_f32_16x16x32_bf16 v[4:7], v[178:181], v[218:221], v[4:7]
	v_mfma_f32_16x16x32_bf16 v[4:7], v[174:177], v[214:217], v[4:7]
	s_setprio 0
	s_barrier
	s_add_i32 s16, s16, 2
	s_add_u32 vcc_lo, vcc_lo, 0x10000
	s_addc_u32 vcc_hi, vcc_hi, 0
	s_add_u32 s14, s14, 0x10000
	s_addc_u32 s15, s15, 0
	s_cmp_gt_u32 s16, 61
	s_cbranch_scc0 .LBB0_535
	s_and_b64 vcc, exec, s[48:49]
	s_cbranch_vccz .LBB0_538
	s_barrier

.LBB0_618:
	v_add_u32_e32 v164, 0x10000, v179
	ds_read_b128 v[182:185], v164
	ds_read_b128 v[186:189], v164 offset:1024
	ds_read_b128 v[190:193], v164 offset:2048
	ds_read_b128 v[194:197], v164 offset:3072
	v_add_u32_e32 v164, 0x14000, v179
	ds_read_b128 v[198:201], v164
	ds_read_b128 v[202:205], v164 offset:1024
	ds_read_b128 v[206:209], v164 offset:2048
	ds_read_b128 v[210:213], v164 offset:3072
	s_cmpk_eq_i32 s18, 0xfc
	s_cselect_b32 s66, s16, s55
	s_cselect_b32 s67, s15, s61
	s_cselect_b32 s64, s17, vcc_lo
	s_cselect_b32 s65, s11, vcc_hi
	s_add_u32 s62, s66, 0x8000
	s_addc_u32 s63, s67, 0
	ds_read_b128 v[214:217], v180
	ds_read_b128 v[218:221], v180 offset:1024
	ds_read_b128 v[222:225], v180 offset:2048
	ds_read_b128 v[226:229], v180 offset:3072
	ds_read_b128 v[230:233], v180 offset:4096
	ds_read_b128 v[234:237], v180 offset:5120
	ds_read_b128 v[238:241], v180 offset:6144
	ds_read_b128 v[242:245], v180 offset:7168
	s_add_u32 s28, s55, 0xffffc000
	s_addc_u32 s29, s61, -1
	s_mov_b32 m0, s47
	s_nop 0
	global_load_lds_dwordx4 v176, s[28:29]
	s_nop 0
	s_mov_b32 m0, s94
	s_nop 0
	global_load_lds_dwordx4 v177, s[28:29]
	s_waitcnt vmcnt(8)
	s_waitcnt lgkmcnt(0)
	s_setprio 1
	s_barrier
	v_mfma_f32_16x16x32_bf16 v[0:3], v[182:185], v[214:217], v[0:3]
	v_mfma_f32_16x16x32_bf16 v[0:3], v[186:189], v[218:221], v[0:3]
	v_mfma_f32_16x16x32_bf16 v[4:7], v[194:197], v[218:221], v[4:7]
	v_mfma_f32_16x16x32_bf16 v[4:7], v[190:193], v[214:217], v[4:7]
	v_mfma_f32_16x16x32_bf16 v[24:27], v[190:193], v[222:225], v[24:27]
	v_mfma_f32_16x16x32_bf16 v[24:27], v[194:197], v[226:229], v[24:27]
	v_mfma_f32_16x16x32_bf16 v[12:15], v[186:189], v[226:229], v[12:15]
	v_mfma_f32_16x16x32_bf16 v[12:15], v[182:185], v[222:225], v[12:15]
	v_mfma_f32_16x16x32_bf16 v[44:47], v[182:185], v[230:233], v[44:47]
	v_mfma_f32_16x16x32_bf16 v[44:47], v[186:189], v[234:237], v[44:47]
	v_mfma_f32_16x16x32_bf16 v[56:59], v[194:197], v[234:237], v[56:59]
	v_mfma_f32_16x16x32_bf16 v[56:59], v[190:193], v[230:233], v[56:59]
	v_mfma_f32_16x16x32_bf16 v[80:83], v[190:193], v[238:241], v[80:83]
	v_mfma_f32_16x16x32_bf16 v[80:83], v[194:197], v[242:245], v[80:83]
	v_mfma_f32_16x16x32_bf16 v[68:71], v[186:189], v[242:245], v[68:71]
	v_mfma_f32_16x16x32_bf16 v[68:71], v[182:185], v[238:241], v[68:71]
	s_setprio 0
	s_setprio 1
	v_mfma_f32_16x16x32_bf16 v[20:23], v[198:201], v[214:217], v[20:23]
	v_mfma_f32_16x16x32_bf16 v[20:23], v[202:205], v[218:221], v[20:23]
	v_mfma_f32_16x16x32_bf16 v[36:39], v[210:213], v[218:221], v[36:39]
	v_mfma_f32_16x16x32_bf16 v[36:39], v[206:209], v[214:217], v[36:39]
	v_mfma_f32_16x16x32_bf16 v[60:63], v[206:209], v[222:225], v[60:63]
	v_mfma_f32_16x16x32_bf16 v[60:63], v[210:213], v[226:229], v[60:63]
	v_mfma_f32_16x16x32_bf16 v[48:51], v[202:205], v[226:229], v[48:51]
	v_mfma_f32_16x16x32_bf16 v[48:51], v[198:201], v[222:225], v[48:51]
	v_mfma_f32_16x16x32_bf16 v[72:75], v[198:201], v[230:233], v[72:75]
	v_mfma_f32_16x16x32_bf16 v[72:75], v[202:205], v[234:237], v[72:75]
	v_mfma_f32_16x16x32_bf16 v[88:91], v[210:213], v[234:237], v[88:91]
	v_mfma_f32_16x16x32_bf16 v[88:91], v[206:209], v[230:233], v[88:91]
	v_mfma_f32_16x16x32_bf16 v[104:107], v[206:209], v[238:241], v[104:107]
	v_mfma_f32_16x16x32_bf16 v[104:107], v[210:213], v[242:245], v[104:107]
	v_mfma_f32_16x16x32_bf16 v[96:99], v[202:205], v[242:245], v[96:99]
	v_mfma_f32_16x16x32_bf16 v[96:99], v[198:201], v[238:241], v[96:99]
	s_setprio 0
	s_barrier
	ds_read_b128 v[214:217], v180 offset:16384
	ds_read_b128 v[218:221], v180 offset:17408
	ds_read_b128 v[222:225], v180 offset:18432
	ds_read_b128 v[226:229], v180 offset:19456
	ds_read_b128 v[230:233], v180 offset:20480
	ds_read_b128 v[234:237], v180 offset:21504
	ds_read_b128 v[238:241], v180 offset:22528
	ds_read_b128 v[242:245], v180 offset:23552
	s_mov_b32 m0, s8
	s_nop 0
	global_load_lds_dwordx4 v176, s[64:65]
	s_add_u32 s28, s64, 0x4000
	s_mov_b32 m0, s20
	s_nop 0
	global_load_lds_dwordx4 v177, s[64:65]
	s_addc_u32 s29, s65, 0
	s_mov_b32 m0, s22
	s_nop 0
	global_load_lds_dwordx4 v176, s[28:29]
	s_nop 0
	s_mov_b32 m0, s24
	s_nop 0
	global_load_lds_dwordx4 v177, s[28:29]
	s_nop 0
	s_mov_b32 m0, s83
	s_nop 0
	global_load_lds_dwordx4 v176, s[66:67]
	s_nop 0
	s_mov_b32 m0, s25
	s_nop 0
	global_load_lds_dwordx4 v177, s[66:67]
	s_waitcnt vmcnt(8)
	s_waitcnt lgkmcnt(0)
	s_setprio 1
	s_barrier
	v_mfma_f32_16x16x32_bf16 v[28:31], v[182:185], v[214:217], v[28:31]
	v_mfma_f32_16x16x32_bf16 v[28:31], v[186:189], v[218:221], v[28:31]
	v_mfma_f32_16x16x32_bf16 v[8:11], v[194:197], v[218:221], v[8:11]
	v_mfma_f32_16x16x32_bf16 v[8:11], v[190:193], v[214:217], v[8:11]
	v_mfma_f32_16x16x32_bf16 v[52:55], v[190:193], v[222:225], v[52:55]
	v_mfma_f32_16x16x32_bf16 v[52:55], v[194:197], v[226:229], v[52:55]
	v_mfma_f32_16x16x32_bf16 v[40:43], v[186:189], v[226:229], v[40:43]
	v_mfma_f32_16x16x32_bf16 v[40:43], v[182:185], v[222:225], v[40:43]
	v_mfma_f32_16x16x32_bf16 v[84:87], v[182:185], v[230:233], v[84:87]
	v_mfma_f32_16x16x32_bf16 v[84:87], v[186:189], v[234:237], v[84:87]
	v_mfma_f32_16x16x32_bf16 v[92:95], v[194:197], v[234:237], v[92:95]
	v_mfma_f32_16x16x32_bf16 v[92:95], v[190:193], v[230:233], v[92:95]
	v_mfma_f32_16x16x32_bf16 v[116:119], v[190:193], v[238:241], v[116:119]
	v_mfma_f32_16x16x32_bf16 v[116:119], v[194:197], v[242:245], v[116:119]
	v_mfma_f32_16x16x32_bf16 v[112:115], v[186:189], v[242:245], v[112:115]
	v_mfma_f32_16x16x32_bf16 v[112:115], v[182:185], v[238:241], v[112:115]
	s_setprio 0
	s_setprio 1
	v_mfma_f32_16x16x32_bf16 v[16:19], v[198:201], v[214:217], v[16:19]
	v_mfma_f32_16x16x32_bf16 v[16:19], v[202:205], v[218:221], v[16:19]
	v_mfma_f32_16x16x32_bf16 v[32:35], v[210:213], v[218:221], v[32:35]
	v_mfma_f32_16x16x32_bf16 v[32:35], v[206:209], v[214:217], v[32:35]
	v_mfma_f32_16x16x32_bf16 v[76:79], v[206:209], v[222:225], v[76:79]
	v_mfma_f32_16x16x32_bf16 v[76:79], v[210:213], v[226:229], v[76:79]
	v_mfma_f32_16x16x32_bf16 v[64:67], v[202:205], v[226:229], v[64:67]
	v_mfma_f32_16x16x32_bf16 v[64:67], v[198:201], v[222:225], v[64:67]
	v_mfma_f32_16x16x32_bf16 v[100:103], v[198:201], v[230:233], v[100:103]
	v_mfma_f32_16x16x32_bf16 v[100:103], v[202:205], v[234:237], v[100:103]
	v_mfma_f32_16x16x32_bf16 v[108:111], v[210:213], v[234:237], v[108:111]
	v_mfma_f32_16x16x32_bf16 v[108:111], v[206:209], v[230:233], v[108:111]
	v_mfma_f32_16x16x32_bf16 v[124:127], v[206:209], v[238:241], v[124:127]
	v_mfma_f32_16x16x32_bf16 v[124:127], v[210:213], v[242:245], v[124:127]
	v_mfma_f32_16x16x32_bf16 v[120:123], v[202:205], v[242:245], v[120:123]
	v_mfma_f32_16x16x32_bf16 v[120:123], v[198:201], v[238:241], v[120:123]
	s_setprio 0
	s_barrier
	v_add_u32_e32 v164, 0x18000, v179
	ds_read_b128 v[182:185], v164
	ds_read_b128 v[186:189], v164 offset:1024
	ds_read_b128 v[190:193], v164 offset:2048
	ds_read_b128 v[194:197], v164 offset:3072
	v_add_u32_e32 v164, 0x1c000, v179
	ds_read_b128 v[198:201], v164
	ds_read_b128 v[202:205], v164 offset:1024
	ds_read_b128 v[206:209], v164 offset:2048
	ds_read_b128 v[210:213], v164 offset:3072
	ds_read_b128 v[214:217], v180 offset:32768
	ds_read_b128 v[218:221], v180 offset:33792
	ds_read_b128 v[222:225], v180 offset:34816
	ds_read_b128 v[226:229], v180 offset:35840
	ds_read_b128 v[230:233], v180 offset:36864
	ds_read_b128 v[234:237], v180 offset:37888
	ds_read_b128 v[238:241], v180 offset:38912
	ds_read_b128 v[242:245], v180 offset:39936
	s_add_u32 s28, s66, 0x4000
	s_addc_u32 s29, s67, 0
	s_mov_b32 m0, s4
	s_nop 0
	global_load_lds_dwordx4 v176, s[28:29]
	s_nop 0
	s_mov_b32 m0, s5
	s_nop 0
	global_load_lds_dwordx4 v177, s[28:29]
	s_waitcnt vmcnt(8)
	s_waitcnt lgkmcnt(0)
	s_setprio 1
	s_barrier
	v_mfma_f32_16x16x32_bf16 v[0:3], v[182:185], v[214:217], v[0:3]
	v_mfma_f32_16x16x32_bf16 v[0:3], v[186:189], v[218:221], v[0:3]
	v_mfma_f32_16x16x32_bf16 v[4:7], v[194:197], v[218:221], v[4:7]
	v_mfma_f32_16x16x32_bf16 v[4:7], v[190:193], v[214:217], v[4:7]
	v_mfma_f32_16x16x32_bf16 v[24:27], v[190:193], v[222:225], v[24:27]
	v_mfma_f32_16x16x32_bf16 v[24:27], v[194:197], v[226:229], v[24:27]
	v_mfma_f32_16x16x32_bf16 v[12:15], v[186:189], v[226:229], v[12:15]
	v_mfma_f32_16x16x32_bf16 v[12:15], v[182:185], v[222:225], v[12:15]
	v_mfma_f32_16x16x32_bf16 v[44:47], v[182:185], v[230:233], v[44:47]
	v_mfma_f32_16x16x32_bf16 v[44:47], v[186:189], v[234:237], v[44:47]
	v_mfma_f32_16x16x32_bf16 v[56:59], v[194:197], v[234:237], v[56:59]
	v_mfma_f32_16x16x32_bf16 v[56:59], v[190:193], v[230:233], v[56:59]
	v_mfma_f32_16x16x32_bf16 v[80:83], v[190:193], v[238:241], v[80:83]
	v_mfma_f32_16x16x32_bf16 v[80:83], v[194:197], v[242:245], v[80:83]
	v_mfma_f32_16x16x32_bf16 v[68:71], v[186:189], v[242:245], v[68:71]
	v_mfma_f32_16x16x32_bf16 v[68:71], v[182:185], v[238:241], v[68:71]
	s_setprio 0
	s_setprio 1
	v_mfma_f32_16x16x32_bf16 v[20:23], v[198:201], v[214:217], v[20:23]
	v_mfma_f32_16x16x32_bf16 v[20:23], v[202:205], v[218:221], v[20:23]
	v_mfma_f32_16x16x32_bf16 v[36:39], v[210:213], v[218:221], v[36:39]
	v_mfma_f32_16x16x32_bf16 v[36:39], v[206:209], v[214:217], v[36:39]
	v_mfma_f32_16x16x32_bf16 v[60:63], v[206:209], v[222:225], v[60:63]
	v_mfma_f32_16x16x32_bf16 v[60:63], v[210:213], v[226:229], v[60:63]
	v_mfma_f32_16x16x32_bf16 v[48:51], v[202:205], v[226:229], v[48:51]
	v_mfma_f32_16x16x32_bf16 v[48:51], v[198:201], v[222:225], v[48:51]
	v_mfma_f32_16x16x32_bf16 v[72:75], v[198:201], v[230:233], v[72:75]
	v_mfma_f32_16x16x32_bf16 v[72:75], v[202:205], v[234:237], v[72:75]
	v_mfma_f32_16x16x32_bf16 v[88:91], v[210:213], v[234:237], v[88:91]
	v_mfma_f32_16x16x32_bf16 v[88:91], v[206:209], v[230:233], v[88:91]
	v_mfma_f32_16x16x32_bf16 v[104:107], v[206:209], v[238:241], v[104:107]
	v_mfma_f32_16x16x32_bf16 v[104:107], v[210:213], v[242:245], v[104:107]
	v_mfma_f32_16x16x32_bf16 v[96:99], v[202:205], v[242:245], v[96:99]
	v_mfma_f32_16x16x32_bf16 v[96:99], v[198:201], v[238:241], v[96:99]
	s_setprio 0
	s_barrier
	ds_read_b128 v[214:217], v180 offset:49152
	ds_read_b128 v[218:221], v180 offset:50176
	ds_read_b128 v[222:225], v180 offset:51200
	ds_read_b128 v[226:229], v180 offset:52224
	ds_read_b128 v[230:233], v180 offset:53248
	ds_read_b128 v[234:237], v180 offset:54272
	ds_read_b128 v[238:241], v180 offset:55296
	ds_read_b128 v[242:245], v180 offset:56320
	s_add_u32 s28, s64, 0x8000
	s_addc_u32 s29, s65, 0
	s_mov_b32 m0, s70
	s_nop 0
	global_load_lds_dwordx4 v176, s[28:29]
	s_nop 0
	s_mov_b32 m0, s71
	s_nop 0
	global_load_lds_dwordx4 v177, s[28:29]
	s_add_u32 s28, s64, 0xc000
	s_addc_u32 s29, s65, 0
	s_mov_b32 m0, s45
	s_nop 0
	global_load_lds_dwordx4 v176, s[28:29]
	s_nop 0
	s_mov_b32 m0, s46
	s_nop 0
	global_load_lds_dwordx4 v177, s[28:29]
	s_nop 0
	s_mov_b32 m0, s72
	s_nop 0
	global_load_lds_dwordx4 v176, s[62:63]
	s_nop 0
	s_mov_b32 m0, s44
	s_nop 0
	global_load_lds_dwordx4 v177, s[62:63]
	s_waitcnt vmcnt(8)
	s_waitcnt lgkmcnt(0)
	s_setprio 1
	s_barrier
	v_mfma_f32_16x16x32_bf16 v[28:31], v[182:185], v[214:217], v[28:31]
	v_mfma_f32_16x16x32_bf16 v[28:31], v[186:189], v[218:221], v[28:31]
	v_mfma_f32_16x16x32_bf16 v[8:11], v[194:197], v[218:221], v[8:11]
	v_mfma_f32_16x16x32_bf16 v[8:11], v[190:193], v[214:217], v[8:11]
	v_mfma_f32_16x16x32_bf16 v[52:55], v[190:193], v[222:225], v[52:55]
	v_mfma_f32_16x16x32_bf16 v[52:55], v[194:197], v[226:229], v[52:55]
	v_mfma_f32_16x16x32_bf16 v[40:43], v[186:189], v[226:229], v[40:43]
	v_mfma_f32_16x16x32_bf16 v[40:43], v[182:185], v[222:225], v[40:43]
	v_mfma_f32_16x16x32_bf16 v[84:87], v[182:185], v[230:233], v[84:87]
	v_mfma_f32_16x16x32_bf16 v[84:87], v[186:189], v[234:237], v[84:87]
	v_mfma_f32_16x16x32_bf16 v[92:95], v[194:197], v[234:237], v[92:95]
	v_mfma_f32_16x16x32_bf16 v[92:95], v[190:193], v[230:233], v[92:95]
	v_mfma_f32_16x16x32_bf16 v[116:119], v[190:193], v[238:241], v[116:119]
	v_mfma_f32_16x16x32_bf16 v[116:119], v[194:197], v[242:245], v[116:119]
	v_mfma_f32_16x16x32_bf16 v[112:115], v[186:189], v[242:245], v[112:115]
	v_mfma_f32_16x16x32_bf16 v[112:115], v[182:185], v[238:241], v[112:115]
	s_setprio 0
	s_setprio 1
	v_mfma_f32_16x16x32_bf16 v[16:19], v[198:201], v[214:217], v[16:19]
	v_mfma_f32_16x16x32_bf16 v[16:19], v[202:205], v[218:221], v[16:19]
	v_mfma_f32_16x16x32_bf16 v[32:35], v[210:213], v[218:221], v[32:35]
	v_mfma_f32_16x16x32_bf16 v[32:35], v[206:209], v[214:217], v[32:35]
	v_mfma_f32_16x16x32_bf16 v[76:79], v[206:209], v[222:225], v[76:79]
	v_mfma_f32_16x16x32_bf16 v[76:79], v[210:213], v[226:229], v[76:79]
	v_mfma_f32_16x16x32_bf16 v[64:67], v[202:205], v[226:229], v[64:67]
	v_mfma_f32_16x16x32_bf16 v[64:67], v[198:201], v[222:225], v[64:67]
	v_mfma_f32_16x16x32_bf16 v[100:103], v[198:201], v[230:233], v[100:103]
	v_mfma_f32_16x16x32_bf16 v[100:103], v[202:205], v[234:237], v[100:103]
	v_mfma_f32_16x16x32_bf16 v[108:111], v[210:213], v[234:237], v[108:111]
	v_mfma_f32_16x16x32_bf16 v[108:111], v[206:209], v[230:233], v[108:111]
	v_mfma_f32_16x16x32_bf16 v[124:127], v[206:209], v[238:241], v[124:127]
	v_mfma_f32_16x16x32_bf16 v[124:127], v[210:213], v[242:245], v[124:127]
	v_mfma_f32_16x16x32_bf16 v[120:123], v[202:205], v[242:245], v[120:123]
	v_mfma_f32_16x16x32_bf16 v[120:123], v[198:201], v[238:241], v[120:123]
	s_setprio 0
	s_barrier
	s_add_i32 s18, s18, 2
	s_add_u32 s55, s55, 0x10000
	s_addc_u32 s61, s61, 0
	s_add_u32 vcc_lo, vcc_lo, 0x10000
	s_addc_u32 vcc_hi, vcc_hi, 0
	s_cmpk_gt_u32 s18, 0xfd
	s_cbranch_scc0 .LBB0_618
	s_and_b64 vcc, exec, s[48:49]
	s_cbranch_vccz .LBB0_621
	s_barrier
	s_andn2_b64 vcc, exec, s[36:37]
	s_cbranch_vccnz .LBB0_623
	s_branch .LBB0_622
